# chunk_unit: all VG^T fragment loads of a block issued up front instead of load-wait-MFMA per fragment; residual-epilogue prologue: gain/scale vector loads batched
# speedup vs baseline: 1.0066x; 1.0066x over previous
.LBB0_342:
	s_load_dwordx4 s[52:55], s[0:1], 0xb8
	v_readlane_b32 s14, v254, 11
	s_nop 1
	v_or_b32_e32 v0, s14, v182
	v_readlane_b32 s14, v254, 32
	s_waitcnt lgkmcnt(0)
	s_add_u32 s17, s54, s14
	v_readlane_b32 s14, v254, 31
	s_addc_u32 s64, s55, s14
	v_readlane_b32 s14, v254, 41
	s_add_u32 s54, s54, s14
	v_readlane_b32 s14, v254, 40
	s_addc_u32 s55, s55, s14
	s_sub_i32 s14, s34, 32
	s_lshr_b32 s14, s14, 2
	s_mul_i32 s14, s14, 9
	s_add_i32 s65, s14, 9
	s_cmp_lt_u32 s34, 32
	s_cselect_b64 s[52:53], -1, 0
	s_and_b64 s[14:15], s[52:53], exec
	s_cselect_b32 s65, 0, s65
	v_readlane_b32 s14, v254, 35
	s_add_i32 s70, s65, s14
	v_lshl_or_b32 v220, s16, 8, v0
	s_lshl_b64 s[14:15], s[70:71], 12
	v_ashrrev_i32_e32 v221, 31, v220
	s_add_u32 s14, s17, s14
	s_addc_u32 s15, s64, s15
	v_lshlrev_b64 v[132:133], 2, v[220:221]
	v_lshl_add_u64 v[130:131], s[14:15], 0, v[132:133]
	global_load_dwordx4 v[146:149], v[130:131], off
	s_cmp_lg_u64 s[12:13], 0
	v_readlane_b32 s17, v254, 42
	s_cselect_b64 s[14:15], -1, 0
	s_add_i32 s70, s17, s65
	s_lshl_b64 s[64:65], s[70:71], 12
	v_lshl_add_u64 v[134:135], s[54:55], 0, v[132:133]
	s_cmp_eq_u64 s[12:13], 0
	v_lshl_add_u64 v[132:133], s[12:13], 0, v[132:133]
	v_lshl_add_u64 v[134:135], v[134:135], 0, s[64:65]
	global_load_dwordx4 v[150:153], v[130:131], off offset:16
	global_load_dwordx4 v[138:141], v[130:131], off offset:512
	global_load_dwordx4 v[142:145], v[130:131], off offset:528
	v_cndmask_b32_e64 v0, 0, 1, s[14:15]
	v_cmp_ne_u32_e64 s[12:13], 1, v0
	s_andn2_b64 vcc, exec, s[14:15]
	s_cbranch_vccnz .LBB0_350
	global_load_dwordx4 v[158:161], v[134:135], off
	global_load_dwordx4 v[174:177], v[132:133], off
	global_load_dwordx4 v[162:165], v[134:135], off offset:16
	global_load_dwordx4 v[216:219], v[132:133], off offset:16
	global_load_dwordx4 v[166:169], v[134:135], off offset:512
	global_load_dwordx4 v[222:225], v[132:133], off offset:512
	global_load_dwordx4 v[170:173], v[134:135], off offset:528
	global_load_dwordx4 v[226:229], v[132:133], off offset:528
	s_waitcnt vmcnt(0)
	v_pk_add_f32 v[160:161], v[160:161], 1.0 op_sel_hi:[1,0]
	v_pk_add_f32 v[158:159], v[158:159], 1.0 op_sel_hi:[1,0]
	v_pk_mul_f32 v[210:211], v[176:177], v[160:161]
	v_pk_mul_f32 v[208:209], v[174:175], v[158:159]
	v_pk_add_f32 v[164:165], v[164:165], 1.0 op_sel_hi:[1,0]
	v_pk_add_f32 v[162:163], v[162:163], 1.0 op_sel_hi:[1,0]
	v_pk_mul_f32 v[214:215], v[218:219], v[164:165]
	v_pk_mul_f32 v[212:213], v[216:217], v[162:163]
	v_pk_add_f32 v[168:169], v[168:169], 1.0 op_sel_hi:[1,0]
	v_pk_add_f32 v[166:167], v[166:167], 1.0 op_sel_hi:[1,0]
	v_pk_mul_f32 v[202:203], v[224:225], v[168:169]
	v_pk_mul_f32 v[200:201], v[222:223], v[166:167]
	v_pk_add_f32 v[172:173], v[172:173], 1.0 op_sel_hi:[1,0]
	v_pk_add_f32 v[170:171], v[170:171], 1.0 op_sel_hi:[1,0]
	v_pk_mul_f32 v[206:207], v[228:229], v[172:173]
	v_pk_mul_f32 v[204:205], v[226:227], v[170:171]

.LBB0_732:
	s_and_b64 vcc, exec, s[20:21]
	s_cbranch_vccz .LBB0_774
	v_readlane_b32 s6, v253, 44
	v_readlane_b32 s8, v253, 45
	v_readlane_b32 s5, v253, 43
	s_ashr_i32 s17, s6, 8
	s_lshl_b32 s6, s8, 5
	s_lshl_b32 s4, s5, 7
	s_and_b32 s16, s6, 0x60
	s_or_b32 s4, s16, s4
	v_readlane_b32 s10, v253, 55
	v_or_b32_e32 v50, s4, v174
	s_lshl_b32 s18, s17, 1
	s_lshl_b32 s7, s10, 2
	v_lshlrev_b32_e32 v2, 5, v174
	v_mov_b32_e32 v3, v1
	v_mov_b32_e32 v133, v1
	v_lshl_add_u64 v[2:3], s[12:13], 0, v[2:3]
	v_ashrrev_i32_e32 v51, 31, v50
	s_add_i32 s4, s18, s7
	s_lshl_b32 s14, s5, 3
	v_lshl_add_u64 v[84:85], v[2:3], 0, v[132:133]
	v_lshlrev_b64 v[2:3], 9, v[50:51]
	s_ashr_i32 s5, s4, 31
	v_lshlrev_b32_e32 v0, 3, v175
	v_lshl_add_u64 v[2:3], s[80:81], 0, v[2:3]
	s_lshl_b64 s[4:5], s[4:5], 7
	v_lshl_add_u64 v[88:89], v[2:3], 0, v[0:1]
	v_mov_b32_e32 v3, s5
	s_and_b32 s5, s8, -4
	v_readlane_b32 s11, v253, 56
	v_or_b32_e32 v92, s16, v174
	s_add_i32 s10, s5, s14
	v_or_b32_e32 v2, s4, v92
	v_readlane_b32 s20, v253, 33
	s_lshl_b32 s4, s17, 7
	s_ashr_i32 s11, s10, 31
	v_lshl_add_u64 v[86:87], s[86:87], 0, v[132:133]
	v_lshlrev_b64 v[4:5], 8, v[2:3]
	v_readlane_b32 s22, v253, 35
	v_readlane_b32 s23, v253, 36
	s_lshl_b64 s[12:13], s[10:11], 13
	s_ashr_i32 s5, s4, 31
	v_lshl_add_u64 v[4:5], v[86:87], 0, v[4:5]
	v_lshl_add_u64 v[2:3], v[2:3], 2, s[22:23]
	v_lshl_add_u64 v[68:69], s[4:5], 1, v[88:89]
	v_lshl_add_u64 v[62:63], v[84:85], 0, s[12:13]
	global_load_dwordx4 v[46:49], v[4:5], off
	global_load_dwordx4 v[42:45], v[4:5], off offset:32
	global_load_dwordx4 v[38:41], v[4:5], off offset:64
	global_load_dwordx4 v[34:37], v[4:5], off offset:96
	global_load_dwordx4 v[30:33], v[4:5], off offset:128
	global_load_dwordx4 v[26:29], v[4:5], off offset:160
	global_load_dwordx4 v[22:25], v[4:5], off offset:192
	global_load_dwordx4 v[18:21], v[4:5], off offset:224
	global_load_dword v82, v[2:3], off
	s_waitcnt lgkmcnt(0)
	global_load_dwordx2 v[56:57], v[68:69], off
	global_load_dwordx2 v[58:59], v[68:69], off offset:16
	global_load_dwordx2 v[60:61], v[68:69], off offset:32
	global_load_dwordx2 v[66:67], v[68:69], off offset:48
	v_add_co_u32_e32 v212, vcc, 0x1000, v62
	s_nop 1
	v_addc_co_u32_e32 v213, vcc, 0, v63, vcc
	v_add_co_u32_e32 v214, vcc, 0x2000, v62
	s_nop 1
	v_addc_co_u32_e32 v215, vcc, 0, v63, vcc
	v_add_co_u32_e32 v216, vcc, 0x3000, v62
	s_nop 1
	v_addc_co_u32_e32 v217, vcc, 0, v63, vcc
	v_add_co_u32_e32 v218, vcc, 0x4000, v62
	s_nop 1
	v_addc_co_u32_e32 v219, vcc, 0, v63, vcc
	v_add_co_u32_e32 v220, vcc, 0x5000, v62
	s_nop 1
	v_addc_co_u32_e32 v221, vcc, 0, v63, vcc
	v_add_co_u32_e32 v222, vcc, 0x6000, v62
	s_nop 1
	v_addc_co_u32_e32 v223, vcc, 0, v63, vcc
	v_add_co_u32_e32 v224, vcc, 0x7000, v62
	s_nop 1
	v_addc_co_u32_e32 v225, vcc, 0, v63, vcc
	global_load_dwordx4 v[134:137], v[62:63], off
	global_load_dwordx4 v[138:141], v[62:63], off offset:1024
	global_load_dwordx4 v[142:145], v[62:63], off offset:2048
	global_load_dwordx4 v[146:149], v[62:63], off offset:3072
	global_load_dwordx4 v[150:153], v[212:213], off
	global_load_dwordx4 v[154:157], v[212:213], off offset:1024
	global_load_dwordx4 v[158:161], v[212:213], off offset:2048
	global_load_dwordx4 v[164:167], v[212:213], off offset:3072
	global_load_dwordx4 v[168:171], v[214:215], off
	global_load_dwordx4 v[176:179], v[214:215], off offset:1024
	global_load_dwordx4 v[192:195], v[214:215], off offset:2048
	global_load_dwordx4 v[196:199], v[214:215], off offset:3072
	global_load_dwordx4 v[200:203], v[216:217], off
	global_load_dwordx4 v[204:207], v[216:217], off offset:1024
	global_load_dwordx4 v[208:211], v[216:217], off offset:2048
	global_load_dwordx4 v[244:247], v[216:217], off offset:3072
	s_movk_i32 s20, 0x1000
	s_or_b32 s10, s10, 1
	s_ashr_i32 s11, s10, 31
	s_lshl_b64 s[10:11], s[10:11], 13
	s_or_b32 s5, s18, 1
	s_lshl_b32 s12, s5, 6
	s_ashr_i32 s13, s12, 31
	v_lshl_add_u64 v[106:107], s[12:13], 1, v[88:89]
	v_readlane_b32 s9, v253, 46
	v_readlane_b32 s21, v253, 34
	v_readlane_b32 s24, v253, 37
	v_readlane_b32 s25, v253, 38
	v_readlane_b32 s26, v253, 39
	v_readlane_b32 s27, v253, 40
	s_waitcnt vmcnt(0)
	v_mfma_f32_32x32x16_bf16 v[2:17], v[134:137], v[46:49], 0
	v_mfma_f32_32x32x16_bf16 v[2:17], v[138:141], v[42:45], v[2:17]
	v_mfma_f32_32x32x16_bf16 v[2:17], v[142:145], v[38:41], v[2:17]
	v_mfma_f32_32x32x16_bf16 v[2:17], v[146:149], v[34:37], v[2:17]
	v_mfma_f32_32x32x16_bf16 v[2:17], v[150:153], v[30:33], v[2:17]
	v_mfma_f32_32x32x16_bf16 v[2:17], v[154:157], v[26:29], v[2:17]
	v_mfma_f32_32x32x16_bf16 v[2:17], v[158:161], v[22:25], v[2:17]
	global_load_dwordx2 v[72:73], v[68:69], off offset:64
	global_load_dwordx2 v[74:75], v[68:69], off offset:80
	global_load_dwordx2 v[80:81], v[68:69], off offset:96
	global_load_dwordx2 v[90:91], v[68:69], off offset:112
	v_lshl_add_u64 v[68:69], v[84:85], 0, s[10:11]
	s_add_i32 s10, s5, s7
	s_ashr_i32 s11, s10, 31
	s_lshl_b64 s[10:11], s[10:11], 7
	s_lshl_b32 s5, s5, 1
	v_mfma_f32_32x32x16_bf16 v[2:17], v[164:167], v[18:21], v[2:17]
	global_load_dwordx4 v[134:137], v[218:219], off
	global_load_dwordx4 v[138:141], v[218:219], off offset:1024
	global_load_dwordx4 v[142:145], v[218:219], off offset:2048
	global_load_dwordx4 v[146:149], v[218:219], off offset:3072
	global_load_dwordx4 v[150:153], v[220:221], off
	global_load_dwordx4 v[154:157], v[220:221], off offset:1024
	global_load_dwordx4 v[158:161], v[220:221], off offset:2048
	global_load_dwordx4 v[164:167], v[220:221], off offset:3072
	v_and_b32_e32 v53, 0xffff0000, v56
	v_lshlrev_b32_e32 v52, 16, v56
	v_and_b32_e32 v55, 0xffff0000, v57
	v_lshlrev_b32_e32 v54, 16, v57
	s_nop 7
	v_pk_add_f32 v[2:3], v[82:83], v[2:3] op_sel_hi:[0,1]
	v_pk_mul_f32 v[52:53], v[2:3], v[52:53]
	v_pk_add_f32 v[4:5], v[82:83], v[4:5] op_sel_hi:[0,1]
	v_mul_f32_e32 v2, v53, v53
	v_pk_fma_f32 v[2:3], v[52:53], v[52:53], v[2:3] op_sel_hi:[1,1,0]
	v_pk_mul_f32 v[54:55], v[4:5], v[54:55]
	v_pk_add_f32 v[6:7], v[82:83], v[6:7] op_sel_hi:[0,1]
	v_pk_fma_f32 v[2:3], v[54:55], v[54:55], v[2:3]
	v_mul_f32_e32 v4, v55, v55
	v_pk_add_f32 v[2:3], v[4:5], v[2:3] op_sel_hi:[0,1]
	v_and_b32_e32 v5, 0xffff0000, v58
	v_lshlrev_b32_e32 v4, 16, v58
	v_pk_mul_f32 v[56:57], v[6:7], v[4:5]
	v_pk_add_f32 v[6:7], v[82:83], v[8:9] op_sel_hi:[0,1]
	v_pk_fma_f32 v[2:3], v[56:57], v[56:57], v[2:3]
	v_mul_f32_e32 v4, v57, v57
	v_pk_add_f32 v[2:3], v[4:5], v[2:3] op_sel_hi:[0,1]
	v_and_b32_e32 v5, 0xffff0000, v59
	v_lshlrev_b32_e32 v4, 16, v59
	v_pk_mul_f32 v[62:63], v[6:7], v[4:5]
	v_pk_add_f32 v[6:7], v[82:83], v[10:11] op_sel_hi:[0,1]
	v_pk_fma_f32 v[2:3], v[62:63], v[62:63], v[2:3]
	v_mul_f32_e32 v4, v63, v63
	v_pk_add_f32 v[2:3], v[4:5], v[2:3] op_sel_hi:[0,1]
	v_and_b32_e32 v5, 0xffff0000, v60
	v_lshlrev_b32_e32 v4, 16, v60
	v_pk_mul_f32 v[58:59], v[6:7], v[4:5]
	v_pk_add_f32 v[6:7], v[82:83], v[12:13] op_sel_hi:[0,1]
	v_pk_fma_f32 v[2:3], v[58:59], v[58:59], v[2:3]
	v_mul_f32_e32 v4, v59, v59
	v_pk_add_f32 v[2:3], v[4:5], v[2:3] op_sel_hi:[0,1]
	v_and_b32_e32 v5, 0xffff0000, v61
	v_lshlrev_b32_e32 v4, 16, v61
	v_pk_mul_f32 v[64:65], v[6:7], v[4:5]
	v_pk_add_f32 v[6:7], v[82:83], v[14:15] op_sel_hi:[0,1]
	v_pk_fma_f32 v[2:3], v[64:65], v[64:65], v[2:3]
	v_mul_f32_e32 v4, v65, v65
	v_pk_add_f32 v[2:3], v[4:5], v[2:3] op_sel_hi:[0,1]
	v_and_b32_e32 v5, 0xffff0000, v66
	v_lshlrev_b32_e32 v4, 16, v66
	v_pk_mul_f32 v[60:61], v[6:7], v[4:5]
	v_pk_add_f32 v[6:7], v[82:83], v[16:17] op_sel_hi:[0,1]
	v_pk_fma_f32 v[2:3], v[60:61], v[60:61], v[2:3]
	v_mul_f32_e32 v4, v61, v61
	v_pk_add_f32 v[2:3], v[4:5], v[2:3] op_sel_hi:[0,1]
	v_and_b32_e32 v5, 0xffff0000, v67
	v_lshlrev_b32_e32 v4, 16, v67
	v_pk_mul_f32 v[66:67], v[6:7], v[4:5]
	s_nop 0
	v_pk_fma_f32 v[2:3], v[66:67], v[66:67], v[2:3]
	v_mul_f32_e32 v4, v67, v67
	v_pk_add_f32 v[70:71], v[4:5], v[2:3] op_sel_hi:[0,1]
	s_waitcnt vmcnt(8)
	v_mfma_f32_32x32x16_bf16 v[2:17], v[168:171], v[46:49], 0
	v_mfma_f32_32x32x16_bf16 v[2:17], v[176:179], v[42:45], v[2:17]
	v_mfma_f32_32x32x16_bf16 v[2:17], v[192:195], v[38:41], v[2:17]
	v_mfma_f32_32x32x16_bf16 v[2:17], v[196:199], v[34:37], v[2:17]
	v_mfma_f32_32x32x16_bf16 v[2:17], v[200:203], v[30:33], v[2:17]
	v_mfma_f32_32x32x16_bf16 v[2:17], v[204:207], v[26:29], v[2:17]
	v_mfma_f32_32x32x16_bf16 v[2:17], v[208:211], v[22:25], v[2:17]
	v_mfma_f32_32x32x16_bf16 v[2:17], v[244:247], v[18:21], v[2:17]
	global_load_dwordx4 v[168:171], v[222:223], off
	global_load_dwordx4 v[176:179], v[222:223], off offset:1024
	global_load_dwordx4 v[192:195], v[222:223], off offset:2048
	global_load_dwordx4 v[196:199], v[222:223], off offset:3072
	global_load_dwordx4 v[200:203], v[224:225], off
	global_load_dwordx4 v[204:207], v[224:225], off offset:1024
	global_load_dwordx4 v[208:211], v[224:225], off offset:2048
	global_load_dwordx4 v[244:247], v[224:225], off offset:3072
	v_and_b32_e32 v19, 0xffff0000, v72
	v_lshlrev_b32_e32 v18, 16, v72
	s_nop 9
	v_pk_add_f32 v[2:3], v[82:83], v[2:3] op_sel_hi:[0,1]
	v_pk_mul_f32 v[68:69], v[2:3], v[18:19]
	v_pk_add_f32 v[4:5], v[82:83], v[4:5] op_sel_hi:[0,1]
	v_pk_fma_f32 v[2:3], v[68:69], v[68:69], v[70:71]
	v_mul_f32_e32 v18, v69, v69
	v_pk_add_f32 v[2:3], v[18:19], v[2:3] op_sel_hi:[0,1]
	v_and_b32_e32 v19, 0xffff0000, v73
	v_lshlrev_b32_e32 v18, 16, v73
	v_pk_mul_f32 v[76:77], v[4:5], v[18:19]
	v_pk_add_f32 v[6:7], v[82:83], v[6:7] op_sel_hi:[0,1]
	v_pk_fma_f32 v[2:3], v[76:77], v[76:77], v[2:3]
	v_mul_f32_e32 v4, v77, v77
	v_pk_add_f32 v[2:3], v[4:5], v[2:3] op_sel_hi:[0,1]
	v_and_b32_e32 v5, 0xffff0000, v74
	v_lshlrev_b32_e32 v4, 16, v74
	v_pk_mul_f32 v[70:71], v[6:7], v[4:5]
	v_pk_add_f32 v[6:7], v[82:83], v[8:9] op_sel_hi:[0,1]
	v_pk_fma_f32 v[2:3], v[70:71], v[70:71], v[2:3]
	v_mul_f32_e32 v4, v71, v71
	v_pk_add_f32 v[2:3], v[4:5], v[2:3] op_sel_hi:[0,1]
	v_and_b32_e32 v5, 0xffff0000, v75
	v_lshlrev_b32_e32 v4, 16, v75
	v_pk_mul_f32 v[78:79], v[6:7], v[4:5]
	v_pk_add_f32 v[6:7], v[82:83], v[10:11] op_sel_hi:[0,1]
	v_pk_fma_f32 v[2:3], v[78:79], v[78:79], v[2:3]
	v_mul_f32_e32 v4, v79, v79
	v_pk_add_f32 v[2:3], v[4:5], v[2:3] op_sel_hi:[0,1]
	v_and_b32_e32 v5, 0xffff0000, v80
	v_lshlrev_b32_e32 v4, 16, v80
	v_pk_mul_f32 v[72:73], v[6:7], v[4:5]
	v_pk_add_f32 v[6:7], v[82:83], v[12:13] op_sel_hi:[0,1]
	v_pk_fma_f32 v[2:3], v[72:73], v[72:73], v[2:3]
	v_mul_f32_e32 v4, v73, v73
	v_pk_add_f32 v[2:3], v[4:5], v[2:3] op_sel_hi:[0,1]
	v_and_b32_e32 v5, 0xffff0000, v81
	v_lshlrev_b32_e32 v4, 16, v81
	v_pk_mul_f32 v[80:81], v[6:7], v[4:5]
	v_pk_add_f32 v[6:7], v[82:83], v[14:15] op_sel_hi:[0,1]
	v_pk_fma_f32 v[2:3], v[80:81], v[80:81], v[2:3]
	v_mul_f32_e32 v4, v81, v81
	v_pk_add_f32 v[2:3], v[4:5], v[2:3] op_sel_hi:[0,1]
	v_and_b32_e32 v5, 0xffff0000, v90
	v_lshlrev_b32_e32 v4, 16, v90
	v_pk_mul_f32 v[74:75], v[6:7], v[4:5]
	v_pk_add_f32 v[6:7], v[82:83], v[16:17] op_sel_hi:[0,1]
	v_pk_fma_f32 v[2:3], v[74:75], v[74:75], v[2:3]
	v_mul_f32_e32 v4, v75, v75
	v_pk_add_f32 v[2:3], v[4:5], v[2:3] op_sel_hi:[0,1]
	v_and_b32_e32 v5, 0xffff0000, v91
	v_lshlrev_b32_e32 v4, 16, v91
	v_pk_mul_f32 v[82:83], v[6:7], v[4:5]
	s_nop 0
	v_pk_fma_f32 v[2:3], v[82:83], v[82:83], v[2:3]
	v_mul_f32_e32 v4, v83, v83
	v_pk_add_f32 v[90:91], v[4:5], v[2:3] op_sel_hi:[0,1]
	v_or_b32_e32 v2, s10, v92
	s_add_i32 s10, s5, s14
	v_mov_b32_e32 v3, s11
	s_ashr_i32 s11, s10, 31
	v_lshlrev_b64 v[4:5], 8, v[2:3]
	s_lshl_b64 s[14:15], s[10:11], 13
	v_lshl_add_u64 v[4:5], v[86:87], 0, v[4:5]
	v_lshl_add_u64 v[2:3], v[2:3], 2, s[22:23]
	v_lshl_add_u64 v[88:89], v[84:85], 0, s[14:15]
	global_load_dwordx4 v[46:49], v[4:5], off
	global_load_dwordx4 v[42:45], v[4:5], off offset:32
	global_load_dwordx4 v[38:41], v[4:5], off offset:64
	global_load_dwordx4 v[34:37], v[4:5], off offset:96
	global_load_dwordx4 v[30:33], v[4:5], off offset:128
	global_load_dwordx4 v[26:29], v[4:5], off offset:160
	global_load_dwordx4 v[22:25], v[4:5], off offset:192
	global_load_dwordx4 v[18:21], v[4:5], off offset:224
	global_load_dword v86, v[2:3], off
	global_load_dwordx2 v[96:97], v[106:107], off
	global_load_dwordx2 v[92:93], v[106:107], off offset:16
	global_load_dwordx2 v[94:95], v[106:107], off offset:32
	global_load_dwordx2 v[102:103], v[106:107], off offset:48
	s_waitcnt vmcnt(0)
	v_mfma_f32_32x32x16_bf16 v[2:17], v[134:137], v[46:49], 0
	s_or_b32 s10, s10, 1
	s_ashr_i32 s11, s10, 31
	s_lshl_b64 s[10:11], s[10:11], 13
	v_lshl_add_u64 v[84:85], v[84:85], 0, s[10:11]
	v_mfma_f32_32x32x16_bf16 v[2:17], v[138:141], v[42:45], v[2:17]
	v_mfma_f32_32x32x16_bf16 v[2:17], v[142:145], v[38:41], v[2:17]
	v_add_co_u32_e32 v88, vcc, s20, v88
	s_nop 1
	v_addc_co_u32_e32 v89, vcc, 0, v89, vcc
	v_mfma_f32_32x32x16_bf16 v[2:17], v[146:149], v[34:37], v[2:17]
	v_mfma_f32_32x32x16_bf16 v[2:17], v[150:153], v[30:33], v[2:17]
	v_mfma_f32_32x32x16_bf16 v[2:17], v[154:157], v[26:29], v[2:17]
	v_mfma_f32_32x32x16_bf16 v[2:17], v[158:161], v[22:25], v[2:17]
	v_and_b32_e32 v89, 0xffff0000, v96
	v_lshlrev_b32_e32 v88, 16, v96
	global_load_dwordx2 v[112:113], v[106:107], off offset:64
	global_load_dwordx2 v[110:111], v[106:107], off offset:80
	global_load_dwordx2 v[108:109], v[106:107], off offset:96
	s_nop 0
	global_load_dwordx2 v[106:107], v[106:107], off offset:112
	v_mfma_f32_32x32x16_bf16 v[2:17], v[164:167], v[18:21], v[2:17]
	s_nop 11
	v_pk_add_f32 v[2:3], v[86:87], v[2:3] op_sel_hi:[0,1]
	v_pk_mul_f32 v[88:89], v[2:3], v[88:89]
	v_pk_add_f32 v[4:5], v[86:87], v[4:5] op_sel_hi:[0,1]
	v_pk_fma_f32 v[2:3], v[88:89], v[88:89], v[90:91]
	v_mul_f32_e32 v90, v89, v89
	v_pk_add_f32 v[2:3], v[90:91], v[2:3] op_sel_hi:[0,1]
	v_and_b32_e32 v91, 0xffff0000, v97
	v_lshlrev_b32_e32 v90, 16, v97
	v_pk_mul_f32 v[96:97], v[4:5], v[90:91]
	v_pk_add_f32 v[6:7], v[86:87], v[6:7] op_sel_hi:[0,1]
	v_pk_fma_f32 v[2:3], v[96:97], v[96:97], v[2:3]
	v_mul_f32_e32 v4, v97, v97
	v_pk_add_f32 v[2:3], v[4:5], v[2:3] op_sel_hi:[0,1]
	v_and_b32_e32 v5, 0xffff0000, v92
	v_lshlrev_b32_e32 v4, 16, v92
	v_pk_mul_f32 v[90:91], v[6:7], v[4:5]
	v_pk_add_f32 v[6:7], v[86:87], v[8:9] op_sel_hi:[0,1]
	v_pk_fma_f32 v[2:3], v[90:91], v[90:91], v[2:3]
	v_mul_f32_e32 v4, v91, v91
	v_pk_add_f32 v[2:3], v[4:5], v[2:3] op_sel_hi:[0,1]
	v_and_b32_e32 v5, 0xffff0000, v93
	v_lshlrev_b32_e32 v4, 16, v93
	v_pk_mul_f32 v[98:99], v[6:7], v[4:5]
	v_pk_add_f32 v[6:7], v[86:87], v[10:11] op_sel_hi:[0,1]
	v_pk_fma_f32 v[2:3], v[98:99], v[98:99], v[2:3]
	v_mul_f32_e32 v4, v99, v99
	v_pk_add_f32 v[2:3], v[4:5], v[2:3] op_sel_hi:[0,1]
	v_and_b32_e32 v5, 0xffff0000, v94
	v_lshlrev_b32_e32 v4, 16, v94
	v_pk_mul_f32 v[92:93], v[6:7], v[4:5]
	v_pk_add_f32 v[6:7], v[86:87], v[12:13] op_sel_hi:[0,1]
	v_pk_fma_f32 v[2:3], v[92:93], v[92:93], v[2:3]
	v_mul_f32_e32 v4, v93, v93
	v_pk_add_f32 v[2:3], v[4:5], v[2:3] op_sel_hi:[0,1]
	v_and_b32_e32 v5, 0xffff0000, v95
	v_lshlrev_b32_e32 v4, 16, v95
	v_pk_mul_f32 v[100:101], v[6:7], v[4:5]
	v_pk_add_f32 v[6:7], v[86:87], v[14:15] op_sel_hi:[0,1]
	v_pk_fma_f32 v[2:3], v[100:101], v[100:101], v[2:3]
	v_mul_f32_e32 v4, v101, v101
	v_pk_add_f32 v[2:3], v[4:5], v[2:3] op_sel_hi:[0,1]
	v_and_b32_e32 v5, 0xffff0000, v102
	v_lshlrev_b32_e32 v4, 16, v102
	v_pk_mul_f32 v[94:95], v[6:7], v[4:5]
	v_pk_add_f32 v[6:7], v[86:87], v[16:17] op_sel_hi:[0,1]
	v_pk_fma_f32 v[2:3], v[94:95], v[94:95], v[2:3]
	v_mul_f32_e32 v4, v95, v95
	v_pk_add_f32 v[2:3], v[4:5], v[2:3] op_sel_hi:[0,1]
	v_and_b32_e32 v5, 0xffff0000, v103
	v_lshlrev_b32_e32 v4, 16, v103
	v_pk_mul_f32 v[102:103], v[6:7], v[4:5]
	s_nop 0
	v_pk_fma_f32 v[2:3], v[102:103], v[102:103], v[2:3]
	v_mul_f32_e32 v4, v103, v103
	v_pk_add_f32 v[104:105], v[4:5], v[2:3] op_sel_hi:[0,1]
	s_waitcnt vmcnt(0)
	v_mfma_f32_32x32x16_bf16 v[2:17], v[168:171], v[46:49], 0
	v_mfma_f32_32x32x16_bf16 v[2:17], v[176:179], v[42:45], v[2:17]
	v_mfma_f32_32x32x16_bf16 v[2:17], v[192:195], v[38:41], v[2:17]
	v_mfma_f32_32x32x16_bf16 v[2:17], v[196:199], v[34:37], v[2:17]
	v_add_co_u32_e32 v38, vcc, s20, v84
	s_nop 1
	v_addc_co_u32_e32 v39, vcc, 0, v85, vcc
	v_cmp_gt_u32_e32 vcc, 32, v238
	v_mfma_f32_32x32x16_bf16 v[2:17], v[200:203], v[30:33], v[2:17]
	v_mfma_f32_32x32x16_bf16 v[2:17], v[204:207], v[26:29], v[2:17]
	v_mfma_f32_32x32x16_bf16 v[2:17], v[208:211], v[22:25], v[2:17]
	v_mfma_f32_32x32x16_bf16 v[2:17], v[244:247], v[18:21], v[2:17]
	v_and_b32_e32 v19, 0xffff0000, v112
	v_lshlrev_b32_e32 v18, 16, v112
	s_nop 9
	v_pk_add_f32 v[2:3], v[86:87], v[2:3] op_sel_hi:[0,1]
	v_pk_mul_f32 v[18:19], v[2:3], v[18:19]
	v_pk_add_f32 v[4:5], v[86:87], v[4:5] op_sel_hi:[0,1]
	v_pk_fma_f32 v[2:3], v[18:19], v[18:19], v[104:105]
	v_mul_f32_e32 v20, v19, v19
	v_pk_add_f32 v[2:3], v[20:21], v[2:3] op_sel_hi:[0,1]
	v_and_b32_e32 v21, 0xffff0000, v113
	v_lshlrev_b32_e32 v20, 16, v113
	v_pk_mul_f32 v[20:21], v[4:5], v[20:21]
	v_pk_add_f32 v[6:7], v[86:87], v[6:7] op_sel_hi:[0,1]
	v_pk_fma_f32 v[2:3], v[20:21], v[20:21], v[2:3]
	v_mul_f32_e32 v4, v21, v21
	v_pk_add_f32 v[2:3], v[4:5], v[2:3] op_sel_hi:[0,1]
	v_and_b32_e32 v5, 0xffff0000, v110
	v_lshlrev_b32_e32 v4, 16, v110
	v_pk_mul_f32 v[6:7], v[6:7], v[4:5]
	v_pk_add_f32 v[8:9], v[86:87], v[8:9] op_sel_hi:[0,1]
	v_pk_fma_f32 v[2:3], v[6:7], v[6:7], v[2:3]
	v_mul_f32_e32 v4, v7, v7
	v_pk_add_f32 v[2:3], v[4:5], v[2:3] op_sel_hi:[0,1]
	v_and_b32_e32 v5, 0xffff0000, v111
	v_lshlrev_b32_e32 v4, 16, v111
	v_pk_mul_f32 v[8:9], v[8:9], v[4:5]
	v_pk_add_f32 v[10:11], v[86:87], v[10:11] op_sel_hi:[0,1]
	v_pk_fma_f32 v[2:3], v[8:9], v[8:9], v[2:3]
	v_mul_f32_e32 v4, v9, v9
	v_pk_add_f32 v[2:3], v[4:5], v[2:3] op_sel_hi:[0,1]
	v_and_b32_e32 v5, 0xffff0000, v108
	v_lshlrev_b32_e32 v4, 16, v108
	v_pk_mul_f32 v[10:11], v[10:11], v[4:5]
	v_pk_add_f32 v[12:13], v[86:87], v[12:13] op_sel_hi:[0,1]
	v_pk_fma_f32 v[2:3], v[10:11], v[10:11], v[2:3]
	v_mul_f32_e32 v4, v11, v11
	v_pk_add_f32 v[2:3], v[4:5], v[2:3] op_sel_hi:[0,1]
	v_and_b32_e32 v5, 0xffff0000, v109
	v_lshlrev_b32_e32 v4, 16, v109
	v_pk_mul_f32 v[12:13], v[12:13], v[4:5]
	v_pk_add_f32 v[14:15], v[86:87], v[14:15] op_sel_hi:[0,1]
	v_pk_fma_f32 v[2:3], v[12:13], v[12:13], v[2:3]
	v_mul_f32_e32 v4, v13, v13
	v_pk_add_f32 v[4:5], v[4:5], v[2:3] op_sel_hi:[0,1]
	v_and_b32_e32 v3, 0xffff0000, v106
	v_lshlrev_b32_e32 v2, 16, v106
	v_pk_mul_f32 v[2:3], v[14:15], v[2:3]
	v_pk_add_f32 v[16:17], v[86:87], v[16:17] op_sel_hi:[0,1]
	v_pk_fma_f32 v[4:5], v[2:3], v[2:3], v[4:5]
	v_mul_f32_e32 v14, v3, v3
	v_pk_add_f32 v[14:15], v[14:15], v[4:5] op_sel_hi:[0,1]
	v_and_b32_e32 v5, 0xffff0000, v107
	v_lshlrev_b32_e32 v4, 16, v107
	v_pk_mul_f32 v[4:5], v[16:17], v[4:5]
	s_nop 0
	v_pk_fma_f32 v[14:15], v[4:5], v[4:5], v[14:15]
	v_mul_f32_e32 v16, v5, v5
	v_pk_add_f32 v[14:15], v[16:17], v[14:15] op_sel_hi:[0,1]
	v_mov_b32_e32 v15, v14
	s_nop 1
	v_permlane32_swap_b32_e32 v14, v15
	s_and_saveexec_b64 s[10:11], vcc
	s_cbranch_execz .LBB0_735
	s_lshl_b32 s5, s17, 9
	s_add_i32 s5, s97, s5
	s_lshl_b32 s12, s16, 2
	s_add_i32 s5, s5, s12
	v_lshl_add_u32 v16, v238, 2, s5
	v_add_f32_e32 v14, v14, v15
	ds_write_b32 v16, v14
